# LDS bank conflicts: combine gate transpose scratch rows padded to 516 dwords (MFMA result ds_write_b32 was 4-way conflicted)
# baseline (speedup 1.0000x reference)
; __device__ void phase_combine(const P& p, int l, int ntok, float* lds) {
;     ...
;     __syncthreads();
;     ...
; #pragma unroll
;         for (int m = 0; m < 96; m += 4) {
; #pragma unroll
;           for (int i = 0; i < 4; ++i) {
;             float4 s = *reinterpret_cast<const float4*>(sig + (i0 + i) * 96 + m);
;             gate[i] += s.x * g2r[m] + s.y * g2r[m + 1] + s.z * g2r[m + 2] + s.w * g2r[m + 3];
;           }
;         }
.LBB0_93:
	s_or_b64 exec, exec, s[0:1]
	s_cmpk_lt_i32 s55, 0x400
	s_movk_i32 s0, 0xfff
	s_cselect_b32 s57, s0, 0xff
	v_readlane_b32 s34, v240, 12
	v_readlane_b32 s62, v240, 14
	s_cselect_b32 s58, 63, 0xff
	s_and_b32 s59, s57, s56
	s_mov_b32 s60, 0
	v_readlane_b32 s35, v240, 13
	v_readlane_b32 s63, v240, 15
	s_mov_b32 s33, 0x800000
	s_movk_i32 s61, 0x3600
	s_mov_b32 s66, 0x88000
	s_mov_b64 s[68:69], 0x3040
	s_waitcnt lgkmcnt(0)
	s_barrier
	v_readfirstlane_b32 s98, v168
	s_lshr_b32 s98, s98, 6
	s_cmp_lt_u32 s98, 4
	s_cbranch_scc0 .Lmf_skip1
	v_and_b32_e32 v241, 15, v168
	v_bfe_u32 v242, v168, 4, 2
	v_mul_u32_u24_e32 v241, 0x184, v241
	v_mul_u32_u24_e32 v243, 0x2000, v242
	v_lshl_add_u32 v241, v242, 2, v241
	v_lshl_add_u32 v243, v168, 2, v243
	ds_read_b32 v244, v241
	ds_read_b32 v245, v241 offset:16
	ds_read_b32 v246, v241 offset:32
	ds_read_b32 v247, v241 offset:48
	ds_read_b32 v248, v241 offset:64
	ds_read_b32 v249, v241 offset:80
	ds_read_b32 v250, v241 offset:96
	ds_read_b32 v251, v241 offset:112
	ds_read_b32 v252, v241 offset:128
	ds_read_b32 v253, v241 offset:144
	ds_read_b32 v254, v241 offset:160
	ds_read_b32 v255, v241 offset:176
	s_waitcnt lgkmcnt(0)
	v_mfma_f32_16x16x4_f32 v[220:223], v244, v90, 0
	v_mfma_f32_16x16x4_f32 v[220:223], v245, v33, v[220:223]
	v_mfma_f32_16x16x4_f32 v[220:223], v246, v80, v[220:223]
	v_mfma_f32_16x16x4_f32 v[220:223], v247, v83, v[220:223]
	v_mfma_f32_16x16x4_f32 v[220:223], v248, v86, v[220:223]
	v_mfma_f32_16x16x4_f32 v[220:223], v249, v89, v[220:223]
	v_mfma_f32_16x16x4_f32 v[220:223], v250, v25, v[220:223]
	v_mfma_f32_16x16x4_f32 v[220:223], v251, v96, v[220:223]
	v_mfma_f32_16x16x4_f32 v[220:223], v252, v97, v[220:223]
	v_mfma_f32_16x16x4_f32 v[220:223], v253, v98, v[220:223]
	v_mfma_f32_16x16x4_f32 v[220:223], v254, v99, v[220:223]
	v_mfma_f32_16x16x4_f32 v[220:223], v255, v100, v[220:223]
	v_mfma_f32_16x16x4_f32 v[224:227], v244, v91, 0
	v_mfma_f32_16x16x4_f32 v[224:227], v245, v78, v[224:227]
	v_mfma_f32_16x16x4_f32 v[224:227], v246, v81, v[224:227]
	v_mfma_f32_16x16x4_f32 v[224:227], v247, v84, v[224:227]
	v_mfma_f32_16x16x4_f32 v[224:227], v248, v87, v[224:227]
	v_mfma_f32_16x16x4_f32 v[224:227], v249, v26, v[224:227]
	v_mfma_f32_16x16x4_f32 v[224:227], v250, v30, v[224:227]
	v_mfma_f32_16x16x4_f32 v[224:227], v251, v34, v[224:227]
	v_mfma_f32_16x16x4_f32 v[224:227], v252, v38, v[224:227]
	v_mfma_f32_16x16x4_f32 v[224:227], v253, v42, v[224:227]
	v_mfma_f32_16x16x4_f32 v[224:227], v254, v46, v[224:227]
	v_mfma_f32_16x16x4_f32 v[224:227], v255, v50, v[224:227]
	v_mfma_f32_16x16x4_f32 v[228:231], v244, v32, 0
	v_mfma_f32_16x16x4_f32 v[228:231], v245, v79, v[228:231]
	v_mfma_f32_16x16x4_f32 v[228:231], v246, v82, v[228:231]
	v_mfma_f32_16x16x4_f32 v[228:231], v247, v85, v[228:231]
	v_mfma_f32_16x16x4_f32 v[228:231], v248, v88, v[228:231]
	v_mfma_f32_16x16x4_f32 v[228:231], v249, v27, v[228:231]
	v_mfma_f32_16x16x4_f32 v[228:231], v250, v31, v[228:231]
	v_mfma_f32_16x16x4_f32 v[228:231], v251, v35, v[228:231]
	v_mfma_f32_16x16x4_f32 v[228:231], v252, v39, v[228:231]
	v_mfma_f32_16x16x4_f32 v[228:231], v253, v43, v[228:231]
	v_mfma_f32_16x16x4_f32 v[228:231], v254, v47, v[228:231]
	v_mfma_f32_16x16x4_f32 v[228:231], v255, v51, v[228:231]
	v_mfma_f32_16x16x4_f32 v[232:235], v244, v92, 0
	v_mfma_f32_16x16x4_f32 v[232:235], v245, v93, v[232:235]
	v_mfma_f32_16x16x4_f32 v[232:235], v246, v11, v[232:235]
	v_mfma_f32_16x16x4_f32 v[232:235], v247, v94, v[232:235]
	v_mfma_f32_16x16x4_f32 v[232:235], v248, v95, v[232:235]
	v_mfma_f32_16x16x4_f32 v[232:235], v249, v24, v[232:235]
	v_mfma_f32_16x16x4_f32 v[232:235], v250, v103, v[232:235]
	v_mfma_f32_16x16x4_f32 v[232:235], v251, v28, v[232:235]
	v_mfma_f32_16x16x4_f32 v[232:235], v252, v29, v[232:235]
	v_mfma_f32_16x16x4_f32 v[232:235], v253, v36, v[232:235]
	v_mfma_f32_16x16x4_f32 v[232:235], v254, v37, v[232:235]
	v_mfma_f32_16x16x4_f32 v[232:235], v255, v40, v[232:235]
	ds_read_b32 v244, v241 offset:192
	ds_read_b32 v245, v241 offset:208
	ds_read_b32 v246, v241 offset:224
	ds_read_b32 v247, v241 offset:240
	ds_read_b32 v248, v241 offset:256
	ds_read_b32 v249, v241 offset:272
	ds_read_b32 v250, v241 offset:288
	ds_read_b32 v251, v241 offset:304
	ds_read_b32 v252, v241 offset:320
	ds_read_b32 v253, v241 offset:336
	ds_read_b32 v254, v241 offset:352
	ds_read_b32 v255, v241 offset:368
	s_waitcnt lgkmcnt(0)
; __device__ void phase_combine(const P& p, int l, int ntok, float* lds) {
;     ...
;       for (int i = 0; i < 4; ++i) {
;         int row = r0 + i0 + i, t = tb + i0 + i;
;         y0[i] = or0[(size_t)row * 512 + tid]; y1[i] = or1[(size_t)row * 512 + tid];
;         const u16* pv = p.projb + (size_t)row * PROJP + O_RKV + 1024 + tid;
;         vc[i] = pv[0]; vp[i] = pv[t > 0 ? -PROJP : 0]; vn[i] = pv[t < T - 1 ? PROJP : 0];
;         sf[i] = p.sbon[(size_t)row * 8 + wv]; sb[i] = p.sbon[(size_t)NT * 8 + (size_t)row * 8 + wv];
;         size_t ob = (size_t)row * 512 + hh * 128 + lane;
;         a0[i] = om0[ob]; a1[i] = om1[ob]; a2[i] = om0[ob + 64]; a3[i] = om1[ob + 64];
;         const u16* pg = p.projb + (size_t)row * PROJP + gch;
;         g0r[i] = pg[0]; g1r[i] = pg[64];
;         cbr[i] = p.projb[(size_t)row * PROJP + O_CB + tid];
;       }
;     ...
; #pragma unroll
;         for (int m = 0; m < 96; m += 4) {
; #pragma unroll
;           for (int i = 0; i < 4; ++i) {
;             float4 s = *reinterpret_cast<const float4*>(sig + (i0 + i) * 96 + m);
;             gate[i] += s.x * g2r[m] + s.y * g2r[m + 1] + s.z * g2r[m + 2] + s.w * g2r[m + 3];
;           }
;         }
	v_mfma_f32_16x16x4_f32 v[220:223], v244, v101, v[220:223]
	v_mfma_f32_16x16x4_f32 v[220:223], v245, v102, v[220:223]
	v_mfma_f32_16x16x4_f32 v[220:223], v246, v45, v[220:223]
	v_mfma_f32_16x16x4_f32 v[220:223], v247, v52, v[220:223]
	v_mfma_f32_16x16x4_f32 v[220:223], v248, v59, v[220:223]
	v_mfma_f32_16x16x4_f32 v[220:223], v249, v66, v[220:223]
	v_mfma_f32_16x16x4_f32 v[220:223], v250, v71, v[220:223]
	v_mfma_f32_16x16x4_f32 v[220:223], v251, v104, v[220:223]
	v_mfma_f32_16x16x4_f32 v[220:223], v252, v107, v[220:223]
	v_mfma_f32_16x16x4_f32 v[220:223], v253, v110, v[220:223]
	v_mfma_f32_16x16x4_f32 v[220:223], v254, v76, v[220:223]
	v_mfma_f32_16x16x4_f32 v[220:223], v255, v114, v[220:223]
	v_mfma_f32_16x16x4_f32 v[224:227], v244, v56, v[224:227]
	v_mfma_f32_16x16x4_f32 v[224:227], v245, v60, v[224:227]
	v_mfma_f32_16x16x4_f32 v[224:227], v246, v48, v[224:227]
	v_mfma_f32_16x16x4_f32 v[224:227], v247, v53, v[224:227]
	v_mfma_f32_16x16x4_f32 v[224:227], v248, v64, v[224:227]
	v_mfma_f32_16x16x4_f32 v[224:227], v249, v67, v[224:227]
	v_mfma_f32_16x16x4_f32 v[224:227], v250, v74, v[224:227]
	v_mfma_f32_16x16x4_f32 v[224:227], v251, v105, v[224:227]
	v_mfma_f32_16x16x4_f32 v[224:227], v252, v108, v[224:227]
	v_mfma_f32_16x16x4_f32 v[224:227], v253, v111, v[224:227]
	v_mfma_f32_16x16x4_f32 v[224:227], v254, v77, v[224:227]
	v_mfma_f32_16x16x4_f32 v[224:227], v255, v115, v[224:227]
	v_mfma_f32_16x16x4_f32 v[228:231], v244, v57, v[228:231]
	v_mfma_f32_16x16x4_f32 v[228:231], v245, v61, v[228:231]
	v_mfma_f32_16x16x4_f32 v[228:231], v246, v49, v[228:231]
	v_mfma_f32_16x16x4_f32 v[228:231], v247, v58, v[228:231]
	v_mfma_f32_16x16x4_f32 v[228:231], v248, v65, v[228:231]
	v_mfma_f32_16x16x4_f32 v[228:231], v249, v70, v[228:231]
	v_mfma_f32_16x16x4_f32 v[228:231], v250, v75, v[228:231]
	v_mfma_f32_16x16x4_f32 v[228:231], v251, v106, v[228:231]
	v_mfma_f32_16x16x4_f32 v[228:231], v252, v109, v[228:231]
	v_mfma_f32_16x16x4_f32 v[228:231], v253, v112, v[228:231]
	v_mfma_f32_16x16x4_f32 v[228:231], v254, v113, v[228:231]
	v_mfma_f32_16x16x4_f32 v[228:231], v255, v117, v[228:231]
	v_mfma_f32_16x16x4_f32 v[232:235], v244, v41, v[232:235]
	v_mfma_f32_16x16x4_f32 v[232:235], v245, v44, v[232:235]
	v_mfma_f32_16x16x4_f32 v[232:235], v246, v54, v[232:235]
	v_mfma_f32_16x16x4_f32 v[232:235], v247, v55, v[232:235]
	v_mfma_f32_16x16x4_f32 v[232:235], v248, v62, v[232:235]
	v_mfma_f32_16x16x4_f32 v[232:235], v249, v63, v[232:235]
	v_mfma_f32_16x16x4_f32 v[232:235], v250, v68, v[232:235]
	v_mfma_f32_16x16x4_f32 v[232:235], v251, v69, v[232:235]
	v_mfma_f32_16x16x4_f32 v[232:235], v252, v72, v[232:235]
	v_mfma_f32_16x16x4_f32 v[232:235], v253, v73, v[232:235]
	v_mfma_f32_16x16x4_f32 v[232:235], v254, v116, v[232:235]
	v_mfma_f32_16x16x4_f32 v[232:235], v255, v118, v[232:235]
	s_nop 7
	s_nop 3
	ds_write_b32 v243, v220 offset:8192
	ds_write_b32 v243, v221 offset:10256
	ds_write_b32 v243, v222 offset:12320
	ds_write_b32 v243, v223 offset:14384
	ds_write_b32 v243, v224 offset:8256
	ds_write_b32 v243, v225 offset:10320
	ds_write_b32 v243, v226 offset:12384
	ds_write_b32 v243, v227 offset:14448
	ds_write_b32 v243, v228 offset:8320
	ds_write_b32 v243, v229 offset:10384
	ds_write_b32 v243, v230 offset:12448
	ds_write_b32 v243, v231 offset:14512
	ds_write_b32 v243, v232 offset:8384
	ds_write_b32 v243, v233 offset:10448
	ds_write_b32 v243, v234 offset:12512
	ds_write_b32 v243, v235 offset:14576
	s_waitcnt lgkmcnt(0)
.Lmf_skip1:
.LBB0_94:
	s_or_b32 s46, s60, s56
	s_ashr_i32 s47, s46, 31
	s_lshl_b64 s[0:1], s[46:47], 9
	s_or_b32 s2, s60, s59
	v_lshl_add_u64 v[0:1], s[0:1], 0, v[4:5]
	s_mul_i32 s20, s46, 0x3600
	v_lshlrev_b64 v[0:1], 1, v[0:1]
	s_mul_hi_i32 s3, s46, 0x3600
	s_add_u32 s22, s94, s20
	v_lshl_add_u64 v[2:3], s[34:35], 0, v[0:1]
	v_lshl_add_u64 v[0:1], s[62:63], 0, v[0:1]
	s_addc_u32 s23, s95, s3
	v_lshlrev_b64 v[22:23], 1, v[4:5]
	v_sub_co_u32_e64 v139, s[52:53], s2, 1
	global_load_ushort v201, v[2:3], off
	global_load_ushort v202, v[0:1], off
	v_lshl_add_u64 v[0:1], s[22:23], 0, v[22:23]
	s_and_b64 s[24:25], s[52:53], exec
	v_add_co_u32_e32 v18, vcc, s75, v0
	s_cselect_b32 s25, 0, -1
	s_cselect_b32 s24, 0, 0xffffca00
	s_cmp_lt_u32 s2, s57
	v_lshl_add_u64 v[2:3], v[0:1], 0, s[68:69]
	v_addc_co_u32_e32 v19, vcc, 0, v1, vcc
	s_cselect_b64 s[44:45], -1, 0
	global_load_ushort v199, v[18:19], off offset:64
	v_lshl_add_u64 v[18:19], v[2:3], 0, s[24:25]
	s_and_b64 s[24:25], s[44:45], exec
	s_cselect_b32 s28, 0x3600, 0
	v_lshl_add_u64 v[2:3], v[2:3], 0, s[28:29]
	s_lshl_b64 s[24:25], s[46:47], 5
	global_load_ushort v208, v[18:19], off
	global_load_ushort v210, v[2:3], off
	s_add_u32 s24, s10, s24
	v_mov_b32_e32 v19, s1
	v_or_b32_e32 v18, s0, v10
	s_addc_u32 s25, s11, s25
	v_lshlrev_b64 v[18:19], 1, v[18:19]
	s_or_b32 s50, s46, 1
	v_lshl_add_u64 v[20:21], v[6:7], 0, v[18:19]
	v_lshl_add_u64 v[18:19], v[8:9], 0, v[18:19]
	s_ashr_i32 s51, s50, 31
	global_load_ushort v195, v[20:21], off
	global_load_ushort v193, v[18:19], off
	global_load_ushort v196, v[20:21], off offset:128
	global_load_ushort v194, v[18:19], off offset:128
	global_load_ushort v192, v134, s[22:23]
	global_load_ushort v191, v134, s[22:23] offset:128
	v_add_co_u32_e32 v18, vcc, s96, v0
	s_or_b32 s3, s2, 1
	s_lshl_b64 s[0:1], s[50:51], 9
	s_mul_i32 s22, s50, 0x3600
	v_addc_co_u32_e32 v19, vcc, 0, v1, vcc
	s_mul_hi_i32 s20, s50, 0x3600
	s_add_u32 s22, s94, s22
	global_load_ushort v138, v[18:19], off offset:3136
	v_lshl_add_u64 v[18:19], s[0:1], 0, v[4:5]
	s_addc_u32 s23, s95, s20
	v_lshlrev_b64 v[18:19], 1, v[18:19]
	s_cmp_lt_u32 s3, s57
	v_lshl_add_u64 v[20:21], s[34:35], 0, v[18:19]
; __device__ void phase_combine(const P& p, int l, int ntok, float* lds) {
;     ...
;       for (int i = 0; i < 4; ++i) {
;         int row = r0 + i0 + i, t = tb + i0 + i;
;         y0[i] = or0[(size_t)row * 512 + tid]; y1[i] = or1[(size_t)row * 512 + tid];
;         const u16* pv = p.projb + (size_t)row * PROJP + O_RKV + 1024 + tid;
;         vc[i] = pv[0]; vp[i] = pv[t > 0 ? -PROJP : 0]; vn[i] = pv[t < T - 1 ? PROJP : 0];
;         sf[i] = p.sbon[(size_t)row * 8 + wv]; sb[i] = p.sbon[(size_t)NT * 8 + (size_t)row * 8 + wv];
;         size_t ob = (size_t)row * 512 + hh * 128 + lane;
;         a0[i] = om0[ob]; a1[i] = om1[ob]; a2[i] = om0[ob + 64]; a3[i] = om1[ob + 64];
;         const u16* pg = p.projb + (size_t)row * PROJP + gch;
;         g0r[i] = pg[0]; g1r[i] = pg[64];
;         cbr[i] = p.projb[(size_t)row * PROJP + O_CB + tid];
;       }
;       {
;         const u16* pc = p.projb + (size_t)(r0 + i0) * PROJP;
; #pragma unroll
;         for (int j = 0; j < 6; ++j) {
;           int t = tb + i0 + j - 1;
;           int off = (t < 0 ? 0 : (t > T - 1 ? T - 1 : t)) - (tb + i0);
;           const u16* pr = pc + (long)off * PROJP;
;           ucc[j] = pr[O_CC + tid]; uch[j] = pr[O_CH + tid];
;         }
	v_lshl_add_u64 v[18:19], s[62:63], 0, v[18:19]
	s_cselect_b64 s[42:43], -1, 0
	v_lshl_add_u64 v[2:3], s[24:25], 0, v[16:17]
	global_load_ushort v212, v[20:21], off
	global_load_ushort v213, v[18:19], off
	v_lshl_add_u64 v[20:21], s[22:23], 0, v[22:23]
	s_and_b64 s[24:25], s[42:43], exec
	v_lshl_add_u64 v[18:19], v[20:21], 0, s[68:69]
	v_add_co_u32_e32 v136, vcc, s75, v20
	s_cselect_b32 s28, 0x3600, 0
	s_nop 0
	v_addc_co_u32_e32 v137, vcc, 0, v21, vcc
	v_lshl_add_u64 v[18:19], v[18:19], 0, s[28:29]
	s_lshl_b64 s[24:25], s[50:51], 5
	global_load_ushort v198, v[136:137], off offset:64
	global_load_ushort v206, v[18:19], off
	s_add_u32 s24, s10, s24
	v_mov_b32_e32 v137, s1
	v_or_b32_e32 v136, s0, v10
	s_addc_u32 s25, s11, s25
	v_lshlrev_b64 v[136:137], 1, v[136:137]
	s_or_b32 s48, s46, 2
	v_lshl_add_u64 v[140:141], v[6:7], 0, v[136:137]
	v_lshl_add_u64 v[136:137], v[8:9], 0, v[136:137]
	s_ashr_i32 s49, s48, 31
	global_load_ushort v167, v[140:141], off
	global_load_ushort v165, v[136:137], off
	global_load_ushort v190, v[140:141], off offset:128
	global_load_ushort v166, v[136:137], off offset:128
	global_load_ushort v164, v134, s[22:23]
	global_load_ushort v163, v134, s[22:23] offset:128
	v_add_co_u32_e32 v20, vcc, s96, v20
	s_or_b32 s23, s2, 2
	s_lshl_b64 s[0:1], s[48:49], 9
	s_mul_i32 s22, s48, 0x3600
	v_lshl_add_u64 v[18:19], s[24:25], 0, v[16:17]
	v_addc_co_u32_e32 v21, vcc, 0, v21, vcc
	s_mul_hi_i32 s20, s48, 0x3600
	s_add_u32 s24, s94, s22
	global_load_ushort v137, v[20:21], off offset:3136
	v_lshl_add_u64 v[20:21], s[0:1], 0, v[4:5]
	s_addc_u32 s25, s95, s20
	v_lshlrev_b64 v[20:21], 1, v[20:21]
	s_cmp_lt_u32 s23, s57
	v_lshl_add_u64 v[140:141], s[34:35], 0, v[20:21]
	v_lshl_add_u64 v[20:21], s[62:63], 0, v[20:21]
	s_cselect_b64 s[40:41], -1, 0
	global_load_ushort v209, v[140:141], off
	global_load_ushort v211, v[20:21], off
	v_lshl_add_u64 v[140:141], s[24:25], 0, v[22:23]
	s_and_b64 s[26:27], s[40:41], exec
	v_lshl_add_u64 v[20:21], v[140:141], 0, s[68:69]
	v_add_co_u32_e32 v142, vcc, s75, v140
	s_cselect_b32 s28, 0x3600, 0
	s_lshl_b64 s[26:27], s[48:49], 5
	v_addc_co_u32_e32 v143, vcc, 0, v141, vcc
	v_lshl_add_u64 v[20:21], v[20:21], 0, s[28:29]
	s_add_u32 s26, s10, s26
	global_load_ushort v197, v[142:143], off offset:64
	global_load_ushort v204, v[20:21], off
	s_addc_u32 s27, s11, s27
	v_mov_b32_e32 v143, s1
	v_or_b32_e32 v142, s0, v10
	s_or_b32 s36, s46, 3
	v_lshlrev_b64 v[142:143], 1, v[142:143]
	v_add_co_u32_e32 v140, vcc, s96, v140
	s_ashr_i32 s37, s36, 31
	v_lshl_add_u64 v[144:145], v[6:7], 0, v[142:143]
	v_lshl_add_u64 v[142:143], v[8:9], 0, v[142:143]
	v_addc_co_u32_e32 v141, vcc, 0, v141, vcc
	s_lshl_b64 s[0:1], s[36:37], 9
	v_lshl_add_u64 v[20:21], s[26:27], 0, v[16:17]
	global_load_ushort v161, v[144:145], off
	global_load_ushort v159, v[142:143], off
	global_load_ushort v162, v[144:145], off offset:128
	global_load_ushort v160, v[142:143], off offset:128
	global_load_ushort v158, v134, s[24:25]
	global_load_ushort v157, v134, s[24:25] offset:128
	global_load_ushort v136, v[140:141], off offset:3136
	s_or_b32 s26, s2, 3
	v_lshl_add_u64 v[140:141], s[0:1], 0, v[4:5]
	s_mul_i32 s22, s36, 0x3600
	v_lshlrev_b64 v[140:141], 1, v[140:141]
	s_mul_hi_i32 s20, s36, 0x3600
	s_add_u32 s24, s94, s22
	v_lshl_add_u64 v[142:143], s[34:35], 0, v[140:141]
	v_lshl_add_u64 v[140:141], s[62:63], 0, v[140:141]
	s_addc_u32 s25, s95, s20
	global_load_ushort v205, v[142:143], off
	global_load_ushort v207, v[140:141], off
	v_lshl_add_u64 v[140:141], s[24:25], 0, v[22:23]
	v_add_co_u32_e32 v142, vcc, s75, v140
	s_cmp_lt_u32 s26, s57
	s_nop 0
	v_addc_co_u32_e32 v143, vcc, 0, v141, vcc
	s_cselect_b64 vcc, -1, 0
	s_and_b64 s[30:31], vcc, exec
	v_lshl_add_u64 v[22:23], v[140:141], 0, s[68:69]
	s_cselect_b32 s28, 0x3600, 0
	v_lshl_add_u64 v[22:23], v[22:23], 0, s[28:29]
	global_load_ushort v200, v[142:143], off offset:64
	global_load_ushort v203, v[22:23], off
	v_mov_b32_e32 v143, s1
	v_or_b32_e32 v142, s0, v10
	v_min_i32_e32 v139, s57, v139
	v_lshlrev_b64 v[142:143], 1, v[142:143]
	v_add_co_u32_e64 v140, s[0:1], s96, v140
	v_cndmask_b32_e64 v139, v139, 0, s[52:53]
	v_lshl_add_u64 v[144:145], v[6:7], 0, v[142:143]
	v_lshl_add_u64 v[142:143], v[8:9], 0, v[142:143]
	v_addc_co_u32_e64 v141, s[0:1], 0, v141, s[0:1]
	v_subrev_u32_e32 v139, s2, v139
	global_load_ushort v155, v[144:145], off
	global_load_ushort v153, v[142:143], off
	global_load_ushort v156, v[144:145], off offset:128
	global_load_ushort v154, v[142:143], off offset:128
	global_load_ushort v152, v134, s[24:25]
	global_load_ushort v149, v134, s[24:25] offset:128
	global_load_ushort v135, v[140:141], off offset:3136
	v_mad_i64_i32 v[140:141], s[0:1], v139, s61, v[0:1]
	v_add_co_u32_e64 v140, s[0:1], s78, v140
	s_lshl_b64 s[30:31], s[36:37], 5
	s_nop 0
	v_addc_co_u32_e64 v141, s[0:1], 0, v141, s[0:1]
	global_load_ushort v139, v[140:141], off offset:64
	s_nop 0
	global_load_ushort v140, v[140:141], off offset:1088
	v_mov_b32_e32 v141, s57
	v_sub_u32_e64 v141, s2, v141 clamp
	v_sub_u32_e32 v141, 0, v141
	v_mad_i64_i32 v[142:143], s[0:1], v141, s61, v[0:1]
	v_add_co_u32_e64 v142, s[0:1], s78, v142
	s_add_u32 s30, s10, s30
	s_nop 0
	v_addc_co_u32_e64 v143, s[0:1], 0, v143, s[0:1]
	s_addc_u32 s31, s11, s31
	s_min_u32 s0, s3, s57
	s_sub_i32 s0, s0, s2
	global_load_ushort v147, v[142:143], off offset:64
	global_load_ushort v148, v[142:143], off offset:1088
	v_mad_i64_i32 v[142:143], s[0:1], s0, v179, v[0:1]
	v_add_co_u32_e64 v142, s[0:1], s78, v142
	v_lshl_add_u64 v[22:23], s[30:31], 0, v[16:17]
	s_nop 0
	v_addc_co_u32_e64 v143, s[0:1], 0, v143, s[0:1]
	s_min_u32 s0, s23, s57
	s_sub_i32 s0, s0, s2
	global_load_ushort v150, v[142:143], off offset:64
	global_load_ushort v151, v[142:143], off offset:1088
	v_mad_i64_i32 v[142:143], s[0:1], s0, v179, v[0:1]
	v_add_co_u32_e64 v142, s[0:1], s78, v142
	s_waitcnt vmcnt(25)
; #define PIN8(a, o) asm volatile("" : "+v"(a[o]), "+v"(a[o + 1]), "+v"(a[o + 2]), "+v"(a[o + 3]), "+v"(a[o + 4]), "+v"(a[o + 5]), "+v"(a[o + 6]), "+v"(a[o + 7]))
; #define PIN8(a) asm volatile("" : "+v"(a[0]), "+v"(a[1]), "+v"(a[2]), "+v"(a[3]))
; __device__ void phase_combine(const P& p, int l, int ntok, float* lds) {
;     ...
; #pragma unroll
;         for (int j = 0; j < 6; ++j) {
;           int t = tb + i0 + j - 1;
;           int off = (t < 0 ? 0 : (t > T - 1 ? T - 1 : t)) - (tb + i0);
;           const u16* pr = pc + (long)off * PROJP;
;           ucc[j] = pr[O_CC + tid]; uch[j] = pr[O_CH + tid];
;         }
;       }
;       PIN8(y0); PIN8(y1); PIN8(sf); PIN8(sb); PIN8(a0); PIN8(a1); PIN8(a2); PIN8(a3);
;       PIN8(vc); PIN8(vp); PIN8(vn); PIN8(g0r); PIN8(g1r); PIN8(cbr); PIN8(ucc); PIN8(uch);
;       asm volatile("" : "+v"(ucc[4]), "+v"(ucc[5]), "+v"(uch[4]), "+v"(uch[5]));
;       {
;         float gate[4];
; #pragma unroll
;         for (int i = 0; i < 4; ++i) gate[i] = 0.f;
; #pragma unroll
;         for (int m = 0; m < 96; m += 4) {
; #pragma unroll
;           for (int i = 0; i < 4; ++i) {
;             float4 s = *reinterpret_cast<const float4*>(sig + (i0 + i) * 96 + m);
;             gate[i] += s.x * g2r[m] + s.y * g2r[m + 1] + s.z * g2r[m + 2] + s.w * g2r[m + 3];
;           }
;         }
	v_mov_b32_e32 v216, v197
	v_addc_co_u32_e64 v143, s[0:1], 0, v143, s[0:1]
	s_min_u32 s0, s26, s57
	s_sub_i32 s0, s0, s2
	global_load_ushort v145, v[142:143], off offset:64
	global_load_ushort v146, v[142:143], off offset:1088
	v_mad_i64_i32 v[142:143], s[0:1], s0, v179, v[0:1]
	v_add_co_u32_e64 v214, s[0:1], s78, v142
	s_nop 1
	v_addc_co_u32_e64 v215, s[0:1], 0, v143, s[0:1]
	s_add_i32 s0, s2, 4
	s_min_u32 s0, s0, s57
	s_sub_i32 s0, s0, s2
	v_mad_i64_i32 v[0:1], s[0:1], s0, v179, v[0:1]
	v_add_co_u32_e64 v0, s[0:1], s78, v0
	global_load_ushort v143, v[214:215], off offset:64
	global_load_ushort v144, v[214:215], off offset:1088
	v_addc_co_u32_e64 v1, s[0:1], 0, v1, s[0:1]
	global_load_ushort v141, v[0:1], off offset:64
	global_load_ushort v142, v[0:1], off offset:1088
	global_load_dword v218, v[2:3], off
	global_load_dword v214, v[22:23], off
	global_load_dword v215, v[20:21], off
	global_load_dword v217, v[18:19], off
	v_add_co_u32_e64 v0, s[0:1], s66, v2
	s_lshl_b64 s[2:3], s[48:49], 12
	s_nop 0
	v_addc_co_u32_e64 v1, s[0:1], 0, v3, s[0:1]
	global_load_dword v219, v[0:1], off
	v_add_co_u32_e64 v0, s[0:1], s66, v22
	s_nop 1
	v_addc_co_u32_e64 v1, s[0:1], 0, v23, s[0:1]
	global_load_dword v22, v[0:1], off
	v_add_co_u32_e64 v0, s[0:1], s66, v20
	s_nop 1
	v_addc_co_u32_e64 v1, s[0:1], 0, v21, s[0:1]
	global_load_dword v23, v[0:1], off
	v_add_co_u32_e64 v0, s[0:1], s66, v18
	v_mov_b32_e32 v21, v198
	s_nop 0
	v_addc_co_u32_e64 v1, s[0:1], 0, v19, s[0:1]
	s_mul_i32 s0, s60, 0x180
	s_add_i32 s0, s0, 0
	global_load_dword v20, v[0:1], off
	v_mov_b32_e32 v18, v199
	v_mov_b32_e32 v19, s0
	s_cmp_lt_u32 s98, 4
	s_cbranch_scc1 .Lmf_skip2
	s_cmp_eq_u32 s60, 0
	s_cbranch_scc0 .Lmf_skip2
	v_and_b32_e32 v241, 15, v168
	v_bfe_u32 v242, v168, 4, 2
	v_mul_u32_u24_e32 v241, 0x184, v241
	v_mul_u32_u24_e32 v243, 0x2000, v242
	v_lshl_add_u32 v241, v242, 2, v241
	v_lshl_add_u32 v243, v168, 2, v243
	ds_read_b32 v244, v241
	ds_read_b32 v245, v241 offset:16
	ds_read_b32 v246, v241 offset:32
	ds_read_b32 v247, v241 offset:48
	ds_read_b32 v248, v241 offset:64
	ds_read_b32 v249, v241 offset:80
	ds_read_b32 v250, v241 offset:96
	ds_read_b32 v251, v241 offset:112
	ds_read_b32 v252, v241 offset:128
	ds_read_b32 v253, v241 offset:144
	ds_read_b32 v254, v241 offset:160
	ds_read_b32 v255, v241 offset:176
	s_waitcnt lgkmcnt(0)
	v_mfma_f32_16x16x4_f32 v[220:223], v244, v90, 0
	v_mfma_f32_16x16x4_f32 v[220:223], v245, v33, v[220:223]
	v_mfma_f32_16x16x4_f32 v[220:223], v246, v80, v[220:223]
	v_mfma_f32_16x16x4_f32 v[220:223], v247, v83, v[220:223]
	v_mfma_f32_16x16x4_f32 v[220:223], v248, v86, v[220:223]
	v_mfma_f32_16x16x4_f32 v[220:223], v249, v89, v[220:223]
	v_mfma_f32_16x16x4_f32 v[220:223], v250, v25, v[220:223]
	v_mfma_f32_16x16x4_f32 v[220:223], v251, v96, v[220:223]
	v_mfma_f32_16x16x4_f32 v[220:223], v252, v97, v[220:223]
	v_mfma_f32_16x16x4_f32 v[220:223], v253, v98, v[220:223]
	v_mfma_f32_16x16x4_f32 v[220:223], v254, v99, v[220:223]
	v_mfma_f32_16x16x4_f32 v[220:223], v255, v100, v[220:223]
	v_mfma_f32_16x16x4_f32 v[224:227], v244, v91, 0
	v_mfma_f32_16x16x4_f32 v[224:227], v245, v78, v[224:227]
	v_mfma_f32_16x16x4_f32 v[224:227], v246, v81, v[224:227]
	v_mfma_f32_16x16x4_f32 v[224:227], v247, v84, v[224:227]
	v_mfma_f32_16x16x4_f32 v[224:227], v248, v87, v[224:227]
	v_mfma_f32_16x16x4_f32 v[224:227], v249, v26, v[224:227]
	v_mfma_f32_16x16x4_f32 v[224:227], v250, v30, v[224:227]
	v_mfma_f32_16x16x4_f32 v[224:227], v251, v34, v[224:227]
	v_mfma_f32_16x16x4_f32 v[224:227], v252, v38, v[224:227]
	v_mfma_f32_16x16x4_f32 v[224:227], v253, v42, v[224:227]
	v_mfma_f32_16x16x4_f32 v[224:227], v254, v46, v[224:227]
	v_mfma_f32_16x16x4_f32 v[224:227], v255, v50, v[224:227]
	v_mfma_f32_16x16x4_f32 v[228:231], v244, v32, 0
	v_mfma_f32_16x16x4_f32 v[228:231], v245, v79, v[228:231]
	v_mfma_f32_16x16x4_f32 v[228:231], v246, v82, v[228:231]
	v_mfma_f32_16x16x4_f32 v[228:231], v247, v85, v[228:231]
	v_mfma_f32_16x16x4_f32 v[228:231], v248, v88, v[228:231]
	v_mfma_f32_16x16x4_f32 v[228:231], v249, v27, v[228:231]
	v_mfma_f32_16x16x4_f32 v[228:231], v250, v31, v[228:231]
	v_mfma_f32_16x16x4_f32 v[228:231], v251, v35, v[228:231]
	v_mfma_f32_16x16x4_f32 v[228:231], v252, v39, v[228:231]
	v_mfma_f32_16x16x4_f32 v[228:231], v253, v43, v[228:231]
	v_mfma_f32_16x16x4_f32 v[228:231], v254, v47, v[228:231]
	v_mfma_f32_16x16x4_f32 v[228:231], v255, v51, v[228:231]
	v_mfma_f32_16x16x4_f32 v[232:235], v244, v92, 0
	v_mfma_f32_16x16x4_f32 v[232:235], v245, v93, v[232:235]
	v_mfma_f32_16x16x4_f32 v[232:235], v246, v11, v[232:235]
	v_mfma_f32_16x16x4_f32 v[232:235], v247, v94, v[232:235]
	v_mfma_f32_16x16x4_f32 v[232:235], v248, v95, v[232:235]
	v_mfma_f32_16x16x4_f32 v[232:235], v249, v24, v[232:235]
	v_mfma_f32_16x16x4_f32 v[232:235], v250, v103, v[232:235]
	v_mfma_f32_16x16x4_f32 v[232:235], v251, v28, v[232:235]
	v_mfma_f32_16x16x4_f32 v[232:235], v252, v29, v[232:235]
	v_mfma_f32_16x16x4_f32 v[232:235], v253, v36, v[232:235]
	v_mfma_f32_16x16x4_f32 v[232:235], v254, v37, v[232:235]
	v_mfma_f32_16x16x4_f32 v[232:235], v255, v40, v[232:235]
	ds_read_b32 v244, v241 offset:192
	ds_read_b32 v245, v241 offset:208
	ds_read_b32 v246, v241 offset:224
	ds_read_b32 v247, v241 offset:240
	ds_read_b32 v248, v241 offset:256
	ds_read_b32 v249, v241 offset:272
	ds_read_b32 v250, v241 offset:288
	ds_read_b32 v251, v241 offset:304
	ds_read_b32 v252, v241 offset:320
	ds_read_b32 v253, v241 offset:336
	ds_read_b32 v254, v241 offset:352
	ds_read_b32 v255, v241 offset:368
	s_waitcnt lgkmcnt(0)
; __device__ __forceinline__ float bf2f(u16 v) { return __uint_as_float(((unsigned)v) << 16); }
; __device__ void phase_combine(const P& p, int l, int ntok, float* lds) {
;     ...
; #pragma unroll
;         for (int i = 0; i < 4; ++i) {
;           int row = r0 + i0 + i, t = tb + i0 + i;
;           float yv = bf2f((u16)y0[i]) + bf2f((u16)y1[i]);
;           float mean = wave_sum_b(yv) * (1.f / 64.f);
;           float d = yv - mean;
;           float var = wave_sum_b(d * d) * (1.f / 64.f);
;           float yn = d * rsqrtf(var + 64e-5f) * gnw + gnb;
	v_mfma_f32_16x16x4_f32 v[220:223], v244, v101, v[220:223]
	v_mfma_f32_16x16x4_f32 v[220:223], v245, v102, v[220:223]
	v_mfma_f32_16x16x4_f32 v[220:223], v246, v45, v[220:223]
	v_mfma_f32_16x16x4_f32 v[220:223], v247, v52, v[220:223]
	v_mfma_f32_16x16x4_f32 v[220:223], v248, v59, v[220:223]
	v_mfma_f32_16x16x4_f32 v[220:223], v249, v66, v[220:223]
	v_mfma_f32_16x16x4_f32 v[220:223], v250, v71, v[220:223]
	v_mfma_f32_16x16x4_f32 v[220:223], v251, v104, v[220:223]
	v_mfma_f32_16x16x4_f32 v[220:223], v252, v107, v[220:223]
	v_mfma_f32_16x16x4_f32 v[220:223], v253, v110, v[220:223]
	v_mfma_f32_16x16x4_f32 v[220:223], v254, v76, v[220:223]
	v_mfma_f32_16x16x4_f32 v[220:223], v255, v114, v[220:223]
	v_mfma_f32_16x16x4_f32 v[224:227], v244, v56, v[224:227]
	v_mfma_f32_16x16x4_f32 v[224:227], v245, v60, v[224:227]
	v_mfma_f32_16x16x4_f32 v[224:227], v246, v48, v[224:227]
	v_mfma_f32_16x16x4_f32 v[224:227], v247, v53, v[224:227]
	v_mfma_f32_16x16x4_f32 v[224:227], v248, v64, v[224:227]
	v_mfma_f32_16x16x4_f32 v[224:227], v249, v67, v[224:227]
	v_mfma_f32_16x16x4_f32 v[224:227], v250, v74, v[224:227]
	v_mfma_f32_16x16x4_f32 v[224:227], v251, v105, v[224:227]
	v_mfma_f32_16x16x4_f32 v[224:227], v252, v108, v[224:227]
	v_mfma_f32_16x16x4_f32 v[224:227], v253, v111, v[224:227]
	v_mfma_f32_16x16x4_f32 v[224:227], v254, v77, v[224:227]
	v_mfma_f32_16x16x4_f32 v[224:227], v255, v115, v[224:227]
	v_mfma_f32_16x16x4_f32 v[228:231], v244, v57, v[228:231]
	v_mfma_f32_16x16x4_f32 v[228:231], v245, v61, v[228:231]
	v_mfma_f32_16x16x4_f32 v[228:231], v246, v49, v[228:231]
	v_mfma_f32_16x16x4_f32 v[228:231], v247, v58, v[228:231]
	v_mfma_f32_16x16x4_f32 v[228:231], v248, v65, v[228:231]
	v_mfma_f32_16x16x4_f32 v[228:231], v249, v70, v[228:231]
	v_mfma_f32_16x16x4_f32 v[228:231], v250, v75, v[228:231]
	v_mfma_f32_16x16x4_f32 v[228:231], v251, v106, v[228:231]
	v_mfma_f32_16x16x4_f32 v[228:231], v252, v109, v[228:231]
	v_mfma_f32_16x16x4_f32 v[228:231], v253, v112, v[228:231]
	v_mfma_f32_16x16x4_f32 v[228:231], v254, v113, v[228:231]
	v_mfma_f32_16x16x4_f32 v[228:231], v255, v117, v[228:231]
	v_mfma_f32_16x16x4_f32 v[232:235], v244, v41, v[232:235]
	v_mfma_f32_16x16x4_f32 v[232:235], v245, v44, v[232:235]
	v_mfma_f32_16x16x4_f32 v[232:235], v246, v54, v[232:235]
	v_mfma_f32_16x16x4_f32 v[232:235], v247, v55, v[232:235]
	v_mfma_f32_16x16x4_f32 v[232:235], v248, v62, v[232:235]
	v_mfma_f32_16x16x4_f32 v[232:235], v249, v63, v[232:235]
	v_mfma_f32_16x16x4_f32 v[232:235], v250, v68, v[232:235]
	v_mfma_f32_16x16x4_f32 v[232:235], v251, v69, v[232:235]
	v_mfma_f32_16x16x4_f32 v[232:235], v252, v72, v[232:235]
	v_mfma_f32_16x16x4_f32 v[232:235], v253, v73, v[232:235]
	v_mfma_f32_16x16x4_f32 v[232:235], v254, v116, v[232:235]
	v_mfma_f32_16x16x4_f32 v[232:235], v255, v118, v[232:235]
	s_nop 7
	s_nop 3
	ds_write_b32 v243, v220 offset:8192
	ds_write_b32 v243, v221 offset:10256
	ds_write_b32 v243, v222 offset:12320
	ds_write_b32 v243, v223 offset:14384
	ds_write_b32 v243, v224 offset:8256
	ds_write_b32 v243, v225 offset:10320
	ds_write_b32 v243, v226 offset:12384
	ds_write_b32 v243, v227 offset:14448
	ds_write_b32 v243, v228 offset:8320
	ds_write_b32 v243, v229 offset:10384
	ds_write_b32 v243, v230 offset:12448
	ds_write_b32 v243, v231 offset:14512
	ds_write_b32 v243, v232 offset:8384
	ds_write_b32 v243, v233 offset:10448
	ds_write_b32 v243, v234 offset:12512
	ds_write_b32 v243, v235 offset:14576
	s_waitcnt lgkmcnt(0)
.Lmf_skip2:
	v_lshlrev_b32_e32 v244, 2, v168
	v_lshl_add_u32 v244, s60, 11, v244
	v_lshl_add_u32 v244, s60, 4, v244
	ds_read_b32 v221, v244 offset:8192
	ds_read_b32 v222, v244 offset:10256
	ds_read_b32 v223, v244 offset:12320
	ds_read_b32 v0, v244 offset:14384
	s_waitcnt vmcnt(30)
	s_waitcnt vmcnt(29)
	s_waitcnt vmcnt(4)
	s_waitcnt vmcnt(0)
	s_waitcnt lgkmcnt(0)
	v_lshlrev_b32_e32 v197, 16, v197
	v_lshlrev_b32_e32 v192, 16, v192
	v_lshlrev_b32_e32 v164, 16, v164
	v_lshlrev_b32_e32 v158, 16, v158
	v_lshlrev_b32_e32 v152, 16, v152
	v_lshlrev_b32_e32 v138, 16, v138
	v_lshlrev_b32_e32 v1, 16, v201
	v_lshlrev_b32_e32 v2, 16, v202
	v_add_f32_e32 v1, v2, v1
	v_mov_b32_e32 v3, v129
	s_nop 0
	v_add_f32_dpp v2, v1, v1 quad_perm:[1,0,3,2] row_mask:0xf bank_mask:0xf bound_ctrl:1
	s_nop 1
	v_add_f32_dpp v2, v2, v2 quad_perm:[2,3,0,1] row_mask:0xf bank_mask:0xf bound_ctrl:1
	s_nop 1
	v_add_f32_dpp v2, v2, v2 row_half_mirror row_mask:0xf bank_mask:0xf bound_ctrl:1
	s_nop 1
	v_add_f32_dpp v2, v2, v2 row_mirror row_mask:0xf bank_mask:0xf bound_ctrl:1
	s_nop 1
	v_mov_b32_dpp v3, v2 row_bcast:15 row_mask:0xa bank_mask:0xf
	v_add_f32_e32 v2, v2, v3
	v_mov_b32_e32 v3, v129
	s_nop 1
	v_mov_b32_dpp v3, v2 row_bcast:31 row_mask:0xc bank_mask:0xf
	v_add_f32_e32 v2, v2, v3
	v_mov_b32_e32 v3, v129
	v_readlane_b32 s0, v2, 63
	s_nop 1
	v_fmac_f32_e32 v1, s0, v180
	v_mul_f32_e32 v2, v1, v1
	s_nop 1
	v_mov_b32_dpp v2, v2 quad_perm:[1,0,3,2] row_mask:0xf bank_mask:0xf bound_ctrl:1
	v_fmac_f32_e32 v2, v1, v1
	s_nop 1
	v_add_f32_dpp v2, v2, v2 quad_perm:[2,3,0,1] row_mask:0xf bank_mask:0xf bound_ctrl:1
	s_nop 1
	v_add_f32_dpp v2, v2, v2 row_half_mirror row_mask:0xf bank_mask:0xf bound_ctrl:1
	s_nop 1
	v_add_f32_dpp v2, v2, v2 row_mirror row_mask:0xf bank_mask:0xf bound_ctrl:1
	s_nop 1
	v_mov_b32_dpp v3, v2 row_bcast:15 row_mask:0xa bank_mask:0xf
	v_add_f32_e32 v2, v2, v3
	v_mov_b32_e32 v3, v129
	s_nop 1
	v_mov_b32_dpp v3, v2 row_bcast:31 row_mask:0xc bank_mask:0xf
	v_add_f32_e32 v2, v2, v3
	s_nop 0
	v_readlane_b32 s0, v2, 63
	s_nop 1
	v_fma_f32 v2, s0, v181, v170
	v_cmp_gt_f32_e64 s[0:1], s33, v2
	v_mul_f32_e32 v3, 0x4b800000, v2
	s_nop 0
	v_cndmask_b32_e64 v2, v2, v3, s[0:1]
	v_rsq_f32_e32 v2, v2
; __device__ __forceinline__ float bf2f(u16 v) { return __uint_as_float(((unsigned)v) << 16); }
; __device__ void phase_combine(const P& p, int l, int ntok, float* lds) {
;     ...
; #pragma unroll
;         for (int i = 0; i < 4; ++i) {
;           int row = r0 + i0 + i, t = tb + i0 + i;
;           float yv = bf2f((u16)y0[i]) + bf2f((u16)y1[i]);
;           float mean = wave_sum_b(yv) * (1.f / 64.f);
;           float d = yv - mean;
;           float var = wave_sum_b(d * d) * (1.f / 64.f);
;           float yn = d * rsqrtf(var + 64e-5f) * gnw + gnb;
;           float v_c = bf2f((u16)vc[i]), v_p = t > 0 ? bf2f((u16)vp[i]) : 0.f, v_n = t < T - 1 ? bf2f((u16)vn[i]) : 0.f;
;           float vf = v_c + (v_p - v_c) * muvf, vb = v_c + (v_n - v_c) * muvb;
;           float bonus = sf[i] * vf + sb[i] * vb;
;           p.nbuf[(size_t)row * D + 1536 + tid] = f2bf((yn + bonus) * gate[i]);
;         }
	s_nop 0
	v_mul_f32_e32 v3, 0x45800000, v2
	v_cndmask_b32_e64 v2, v2, v3, s[0:1]
	v_mul_f32_e32 v1, v1, v2
	v_lshlrev_b32_e32 v2, 16, v18
	v_lshlrev_b32_e32 v3, 16, v208
	v_lshlrev_b32_e32 v18, 16, v210
	v_cndmask_b32_e64 v3, v3, 0, s[52:53]
	v_cndmask_b32_e64 v18, 0, v18, s[44:45]
	v_sub_f32_e32 v3, v3, v2
	v_sub_f32_e32 v18, v18, v2
	v_fma_f32 v3, v121, v3, v2
	v_fmac_f32_e32 v2, v122, v18
	v_mul_f32_e32 v2, v219, v2
	v_fma_f32 v1, v119, v1, v120
	v_fmac_f32_e32 v2, v218, v3
	v_add_f32_e32 v1, v2, v1
	v_mul_f32_e32 v1, v221, v1
	v_bfe_u32 v2, v1, 16, 1
	s_lshl_b64 s[44:45], s[46:47], 12
	v_add3_u32 v1, v1, v2, s21
	v_lshl_add_u64 v[18:19], v[14:15], 0, s[44:45]
	global_store_short_d16_hi v[18:19], v1, off offset:3072
	v_lshlrev_b32_e32 v1, 16, v212
	v_lshlrev_b32_e32 v2, 16, v213
	v_add_f32_e32 v1, v2, v1
	v_mov_b32_e32 v3, v129
	s_nop 0
	v_add_f32_dpp v2, v1, v1 quad_perm:[1,0,3,2] row_mask:0xf bank_mask:0xf bound_ctrl:1
	s_nop 1
	v_add_f32_dpp v2, v2, v2 quad_perm:[2,3,0,1] row_mask:0xf bank_mask:0xf bound_ctrl:1
	s_nop 1
	v_add_f32_dpp v2, v2, v2 row_half_mirror row_mask:0xf bank_mask:0xf bound_ctrl:1
	s_nop 1
	v_add_f32_dpp v2, v2, v2 row_mirror row_mask:0xf bank_mask:0xf bound_ctrl:1
	s_nop 1
	v_mov_b32_dpp v3, v2 row_bcast:15 row_mask:0xa bank_mask:0xf
	v_add_f32_e32 v2, v2, v3
	v_mov_b32_e32 v3, v129
	s_nop 1
	v_mov_b32_dpp v3, v2 row_bcast:31 row_mask:0xc bank_mask:0xf
	v_add_f32_e32 v2, v2, v3
	v_mov_b32_e32 v3, v129
	v_readlane_b32 s0, v2, 63
	s_nop 1
	v_fmac_f32_e32 v1, s0, v180
	v_mul_f32_e32 v2, v1, v1
	s_nop 1
	v_mov_b32_dpp v2, v2 quad_perm:[1,0,3,2] row_mask:0xf bank_mask:0xf bound_ctrl:1
	v_fmac_f32_e32 v2, v1, v1
	s_nop 1
	v_add_f32_dpp v2, v2, v2 quad_perm:[2,3,0,1] row_mask:0xf bank_mask:0xf bound_ctrl:1
	s_nop 1
	v_add_f32_dpp v2, v2, v2 row_half_mirror row_mask:0xf bank_mask:0xf bound_ctrl:1
	s_nop 1
	v_add_f32_dpp v2, v2, v2 row_mirror row_mask:0xf bank_mask:0xf bound_ctrl:1
	s_nop 1
	v_mov_b32_dpp v3, v2 row_bcast:15 row_mask:0xa bank_mask:0xf
	v_add_f32_e32 v2, v2, v3
	v_mov_b32_e32 v3, v129
	s_nop 1
	v_mov_b32_dpp v3, v2 row_bcast:31 row_mask:0xc bank_mask:0xf
	v_add_f32_e32 v2, v2, v3
	s_nop 0
	v_readlane_b32 s0, v2, 63
	s_nop 1
	v_fma_f32 v2, s0, v181, v170
	v_cmp_gt_f32_e64 s[0:1], s33, v2
	v_mul_f32_e32 v3, 0x4b800000, v2
	s_nop 0
	v_cndmask_b32_e64 v2, v2, v3, s[0:1]
	v_rsq_f32_e32 v2, v2
	s_nop 0
	v_mul_f32_e32 v3, 0x45800000, v2
	v_cndmask_b32_e64 v2, v2, v3, s[0:1]
	v_mul_f32_e32 v1, v1, v2
	v_lshlrev_b32_e32 v2, 16, v21
	v_lshlrev_b32_e32 v21, 16, v206
	v_lshlrev_b32_e32 v3, 16, v199
	v_cndmask_b32_e64 v21, 0, v21, s[42:43]
	v_sub_f32_e32 v3, v3, v2
	v_sub_f32_e32 v21, v21, v2
	v_fma_f32 v3, v121, v3, v2
	v_fmac_f32_e32 v2, v122, v21
	v_mul_f32_e32 v2, v20, v2
	v_fma_f32 v1, v119, v1, v120
	v_fmac_f32_e32 v2, v217, v3
	v_add_f32_e32 v1, v2, v1
	v_mul_f32_e32 v1, v222, v1
	v_bfe_u32 v2, v1, 16, 1
	s_lshl_b64 s[42:43], s[50:51], 12
	v_add3_u32 v1, v1, v2, s21
	v_lshl_add_u64 v[20:21], v[14:15], 0, s[42:43]
	global_store_short_d16_hi v[20:21], v1, off offset:3072
	v_lshlrev_b32_e32 v1, 16, v209
	v_lshlrev_b32_e32 v2, 16, v211
	v_add_f32_e32 v1, v2, v1
	v_mov_b32_e32 v3, v129
	s_nop 0
	v_add_f32_dpp v2, v1, v1 quad_perm:[1,0,3,2] row_mask:0xf bank_mask:0xf bound_ctrl:1
	s_nop 1
	v_add_f32_dpp v2, v2, v2 quad_perm:[2,3,0,1] row_mask:0xf bank_mask:0xf bound_ctrl:1
	s_nop 1
	v_add_f32_dpp v2, v2, v2 row_half_mirror row_mask:0xf bank_mask:0xf bound_ctrl:1
	s_nop 1
	v_add_f32_dpp v2, v2, v2 row_mirror row_mask:0xf bank_mask:0xf bound_ctrl:1
	s_nop 1
	v_mov_b32_dpp v3, v2 row_bcast:15 row_mask:0xa bank_mask:0xf
	v_add_f32_e32 v2, v2, v3
	v_mov_b32_e32 v3, v129
	s_nop 1
	v_mov_b32_dpp v3, v2 row_bcast:31 row_mask:0xc bank_mask:0xf
	v_add_f32_e32 v2, v2, v3
	v_mov_b32_e32 v3, v129
	v_readlane_b32 s0, v2, 63
	s_nop 1
	v_fmac_f32_e32 v1, s0, v180
	v_mul_f32_e32 v2, v1, v1
	s_nop 1
	v_mov_b32_dpp v2, v2 quad_perm:[1,0,3,2] row_mask:0xf bank_mask:0xf bound_ctrl:1
	v_fmac_f32_e32 v2, v1, v1
	s_nop 1
	v_add_f32_dpp v2, v2, v2 quad_perm:[2,3,0,1] row_mask:0xf bank_mask:0xf bound_ctrl:1
	s_nop 1
	v_add_f32_dpp v2, v2, v2 row_half_mirror row_mask:0xf bank_mask:0xf bound_ctrl:1
	s_nop 1
	v_add_f32_dpp v2, v2, v2 row_mirror row_mask:0xf bank_mask:0xf bound_ctrl:1
	s_nop 1
	v_mov_b32_dpp v3, v2 row_bcast:15 row_mask:0xa bank_mask:0xf
	v_add_f32_e32 v2, v2, v3
	v_mov_b32_e32 v3, v129
	s_nop 1
	v_mov_b32_dpp v3, v2 row_bcast:31 row_mask:0xc bank_mask:0xf
	v_add_f32_e32 v2, v2, v3
	s_nop 0
	v_readlane_b32 s0, v2, 63
	s_nop 1
	v_fma_f32 v2, s0, v181, v170
	v_cmp_gt_f32_e64 s[0:1], s33, v2
	v_mul_f32_e32 v3, 0x4b800000, v2
	s_nop 0
	v_cndmask_b32_e64 v2, v2, v3, s[0:1]
	v_rsq_f32_e32 v2, v2
	s_nop 0
	v_mul_f32_e32 v3, 0x45800000, v2
	v_cndmask_b32_e64 v2, v2, v3, s[0:1]
	v_lshlrev_b32_e32 v3, 16, v198
	v_lshlrev_b32_e32 v198, 16, v204
	v_mul_f32_e32 v1, v1, v2
	v_lshlrev_b32_e32 v2, 16, v216
	v_cndmask_b32_e64 v198, 0, v198, s[40:41]
	v_sub_f32_e32 v3, v3, v2
	v_sub_f32_e32 v198, v198, v2
	v_fma_f32 v3, v121, v3, v2
	v_fmac_f32_e32 v2, v122, v198
	v_mul_f32_e32 v2, v23, v2
	v_fma_f32 v1, v119, v1, v120
	v_fmac_f32_e32 v2, v215, v3
	v_add_f32_e32 v1, v2, v1
	v_mul_f32_e32 v1, v223, v1
	v_bfe_u32 v2, v1, 16, 1
	v_add3_u32 v1, v1, v2, s21
	v_lshl_add_u64 v[2:3], v[14:15], 0, s[2:3]
	global_store_short_d16_hi v[2:3], v1, off offset:3072
	v_lshlrev_b32_e32 v1, 16, v205
	v_lshlrev_b32_e32 v23, 16, v207
	v_add_f32_e32 v1, v23, v1
	v_mov_b32_e32 v198, v129
	s_nop 0
	v_add_f32_dpp v23, v1, v1 quad_perm:[1,0,3,2] row_mask:0xf bank_mask:0xf bound_ctrl:1
	s_nop 1
	v_add_f32_dpp v23, v23, v23 quad_perm:[2,3,0,1] row_mask:0xf bank_mask:0xf bound_ctrl:1
; __device__ __forceinline__ float bf2f(u16 v) { return __uint_as_float(((unsigned)v) << 16); }
; __device__ __forceinline__ float siluf_(float x) { return x / (1.f + __expf(-x)); }
; __device__ void phase_combine(const P& p, int l, int ntok, float* lds) {
;     ...
; #pragma unroll
;         for (int i = 0; i < 4; ++i) {
;           int row = r0 + i0 + i, t = tb + i0 + i;
;           float yv = bf2f((u16)y0[i]) + bf2f((u16)y1[i]);
;           float mean = wave_sum_b(yv) * (1.f / 64.f);
;           float d = yv - mean;
;           float var = wave_sum_b(d * d) * (1.f / 64.f);
;           float yn = d * rsqrtf(var + 64e-5f) * gnw + gnb;
;           float v_c = bf2f((u16)vc[i]), v_p = t > 0 ? bf2f((u16)vp[i]) : 0.f, v_n = t < T - 1 ? bf2f((u16)vn[i]) : 0.f;
;           float vf = v_c + (v_p - v_c) * muvf, vb = v_c + (v_n - v_c) * muvb;
;           float bonus = sf[i] * vf + sb[i] * vb;
;           p.nbuf[(size_t)row * D + 1536 + tid] = f2bf((yn + bonus) * gate[i]);
;         }
;       }
; #pragma unroll
;       for (int i = 0; i < 4; ++i) {
;         int row = r0 + i0 + i;
;         float o0 = bf2f((u16)a0[i]) + bf2f((u16)a1[i]), o1 = bf2f((u16)a2[i]) + bf2f((u16)a3[i]);
;         float ss = wave_sum_b(o0 * o0 + o1 * o1);
;         float rstd = rsqrtf(ss * (1.f / 128.f) + 1e-6f);
;         u16* dst = p.nbuf + (size_t)row * D + mixer * 512 + hh * 128 + lane;
;         dst[0] = f2bf(o0 * rstd * ng0 * siluf_(bf2f((u16)g0r[i])));
;         dst[64] = f2bf(o1 * rstd * ng1 * siluf_(bf2f((u16)g1r[i])));
;       }
	s_nop 1
	v_add_f32_dpp v23, v23, v23 row_half_mirror row_mask:0xf bank_mask:0xf bound_ctrl:1
	s_nop 1
	v_add_f32_dpp v23, v23, v23 row_mirror row_mask:0xf bank_mask:0xf bound_ctrl:1
	s_nop 1
	v_mov_b32_dpp v198, v23 row_bcast:15 row_mask:0xa bank_mask:0xf
	v_add_f32_e32 v23, v23, v198
	v_mov_b32_e32 v198, v129
	s_nop 1
	v_mov_b32_dpp v198, v23 row_bcast:31 row_mask:0xc bank_mask:0xf
	v_add_f32_e32 v23, v23, v198
	v_mov_b32_e32 v198, v129
	v_readlane_b32 s0, v23, 63
	s_nop 1
	v_fmac_f32_e32 v1, s0, v180
	v_mul_f32_e32 v23, v1, v1
	s_nop 1
	v_mov_b32_dpp v23, v23 quad_perm:[1,0,3,2] row_mask:0xf bank_mask:0xf bound_ctrl:1
	v_fmac_f32_e32 v23, v1, v1
	s_nop 1
	v_add_f32_dpp v23, v23, v23 quad_perm:[2,3,0,1] row_mask:0xf bank_mask:0xf bound_ctrl:1
	s_nop 1
	v_add_f32_dpp v23, v23, v23 row_half_mirror row_mask:0xf bank_mask:0xf bound_ctrl:1
	s_nop 1
	v_add_f32_dpp v23, v23, v23 row_mirror row_mask:0xf bank_mask:0xf bound_ctrl:1
	s_nop 1
	v_mov_b32_dpp v198, v23 row_bcast:15 row_mask:0xa bank_mask:0xf
	v_add_f32_e32 v23, v23, v198
	v_mov_b32_e32 v198, v129
	s_nop 1
	v_mov_b32_dpp v198, v23 row_bcast:31 row_mask:0xc bank_mask:0xf
	v_add_f32_e32 v23, v23, v198
	s_nop 0
	v_readlane_b32 s0, v23, 63
	s_nop 1
	v_fma_f32 v23, s0, v181, v170
	v_cmp_gt_f32_e64 s[0:1], s33, v23
	v_mul_f32_e32 v198, 0x4b800000, v23
	s_nop 0
	v_cndmask_b32_e64 v23, v23, v198, s[0:1]
	v_rsq_f32_e32 v23, v23
	s_nop 0
	v_mul_f32_e32 v198, 0x45800000, v23
	v_cndmask_b32_e64 v23, v23, v198, s[0:1]
	v_lshlrev_b32_e32 v198, 16, v203
	v_mul_f32_e32 v1, v1, v23
	v_lshlrev_b32_e32 v23, 16, v200
	v_cndmask_b32_e32 v198, 0, v198, vcc
	v_sub_f32_e32 v197, v197, v23
	v_sub_f32_e32 v198, v198, v23
	v_fma_f32 v197, v121, v197, v23
	v_fmac_f32_e32 v23, v122, v198
	v_mul_f32_e32 v22, v22, v23
	v_fma_f32 v1, v119, v1, v120
	v_fmac_f32_e32 v22, v214, v197
	v_add_f32_e32 v1, v22, v1
	v_mul_f32_e32 v0, v0, v1
	v_bfe_u32 v1, v0, 16, 1
	s_lshl_b64 s[0:1], s[36:37], 12
	v_add3_u32 v22, v0, v1, s21
	v_lshl_add_u64 v[0:1], v[14:15], 0, s[0:1]
	global_store_short_d16_hi v[0:1], v22, off offset:3072
	v_lshlrev_b32_e32 v22, 16, v195
	v_lshlrev_b32_e32 v23, 16, v196
	v_lshlrev_b32_e32 v196, 16, v193
	v_lshlrev_b32_e32 v197, 16, v194
	v_pk_add_f32 v[22:23], v[22:23], v[196:197]
	v_mul_f32_e32 v196, 0xbfb8aa3b, v192
	v_pk_mul_f32 v[194:195], v[22:23], v[22:23]
	v_exp_f32_e32 v196, v196
	v_add_f32_e32 v193, v194, v195
	v_mov_b32_e32 v194, v129
	v_add_f32_e32 v196, 1.0, v196
	v_add_f32_dpp v193, v193, v193 quad_perm:[1,0,3,2] row_mask:0xf bank_mask:0xf bound_ctrl:1
	s_nop 0
	s_nop 0
	v_add_f32_dpp v193, v193, v193 quad_perm:[2,3,0,1] row_mask:0xf bank_mask:0xf bound_ctrl:1
	s_nop 0
	s_nop 0
	v_add_f32_dpp v193, v193, v193 row_half_mirror row_mask:0xf bank_mask:0xf bound_ctrl:1
	s_nop 0
	s_nop 0
	v_add_f32_dpp v193, v193, v193 row_mirror row_mask:0xf bank_mask:0xf bound_ctrl:1
	s_nop 0
	s_nop 0
	v_mov_b32_dpp v194, v193 row_bcast:15 row_mask:0xa bank_mask:0xf
	v_add_f32_e32 v193, v193, v194
	v_mov_b32_e32 v194, v129
	s_nop 1
	v_mov_b32_dpp v194, v193 row_bcast:31 row_mask:0xc bank_mask:0xf
	v_add_f32_e32 v193, v193, v194
	s_nop 0
	v_readlane_b32 s20, v193, 63
	s_nop 1
	v_fma_f32 v193, s20, v182, v169
	v_cmp_gt_f32_e32 vcc, s33, v193
	v_mul_f32_e32 v194, 0x4b800000, v193
	s_nop 0
	v_cndmask_b32_e32 v193, v193, v194, vcc
	v_rsq_f32_e32 v193, v193
	s_nop 0
	v_mul_f32_e32 v194, 0x45800000, v193
	v_cndmask_b32_e32 v193, v193, v194, vcc
	v_mul_f32_e32 v22, v22, v193
	v_mul_f32_e32 v22, v126, v22
	v_rcp_f32_e32 v197, v196
	s_nop 0
	v_mul_f32_e32 v192, v192, v197
	v_mul_f32_e32 v22, v192, v22
	v_bfe_u32 v192, v22, 16, 1
	v_lshl_add_u64 v[194:195], v[12:13], 0, s[44:45]
	v_add3_u32 v22, v22, v192, s21
	global_store_short_d16_hi v[194:195], v22, off
	v_mul_f32_e32 v22, v23, v193
	v_lshlrev_b32_e32 v23, 16, v191
	v_mul_f32_e32 v191, 0xbfb8aa3b, v23
	v_exp_f32_e32 v191, v191
	v_mul_f32_e32 v22, v127, v22
	v_add_f32_e32 v191, 1.0, v191
	s_nop 0
	v_rcp_f32_e32 v192, v191
	s_nop 0
	v_mul_f32_e32 v23, v23, v192
	v_mul_f32_e32 v22, v23, v22
	v_bfe_u32 v23, v22, 16, 1
	v_add3_u32 v22, v22, v23, s21
	global_store_short_d16_hi v[194:195], v22, off offset:128
	v_lshlrev_b32_e32 v22, 16, v167
	v_lshlrev_b32_e32 v23, 16, v190
	v_lshlrev_b32_e32 v190, 16, v165
	v_lshlrev_b32_e32 v191, 16, v166
	v_pk_add_f32 v[22:23], v[22:23], v[190:191]
	v_mul_f32_e32 v190, 0xbfb8aa3b, v164
	v_pk_mul_f32 v[166:167], v[22:23], v[22:23]
	v_exp_f32_e32 v190, v190
	v_add_f32_e32 v165, v166, v167
	v_mov_b32_e32 v166, v129
	v_add_f32_e32 v190, 1.0, v190
	v_add_f32_dpp v165, v165, v165 quad_perm:[1,0,3,2] row_mask:0xf bank_mask:0xf bound_ctrl:1
	s_nop 0
	s_nop 0
	v_add_f32_dpp v165, v165, v165 quad_perm:[2,3,0,1] row_mask:0xf bank_mask:0xf bound_ctrl:1
	s_nop 0
	s_nop 0
	v_add_f32_dpp v165, v165, v165 row_half_mirror row_mask:0xf bank_mask:0xf bound_ctrl:1
	s_nop 0
	s_nop 0
	v_add_f32_dpp v165, v165, v165 row_mirror row_mask:0xf bank_mask:0xf bound_ctrl:1
	s_nop 0
	s_nop 0
	v_mov_b32_dpp v166, v165 row_bcast:15 row_mask:0xa bank_mask:0xf
	v_add_f32_e32 v165, v165, v166
	v_mov_b32_e32 v166, v129
	s_nop 1
	v_mov_b32_dpp v166, v165 row_bcast:31 row_mask:0xc bank_mask:0xf
	v_add_f32_e32 v165, v165, v166
	s_nop 0
	v_readlane_b32 s20, v165, 63
	s_nop 1
	v_fma_f32 v165, s20, v182, v169
	v_cmp_gt_f32_e32 vcc, s33, v165
	v_mul_f32_e32 v166, 0x4b800000, v165
	s_nop 0
	v_cndmask_b32_e32 v165, v165, v166, vcc
	v_rsq_f32_e32 v165, v165
	s_nop 0
	v_mul_f32_e32 v166, 0x45800000, v165
	v_cndmask_b32_e32 v165, v165, v166, vcc
	v_mul_f32_e32 v22, v22, v165
	v_mul_f32_e32 v22, v126, v22
	v_rcp_f32_e32 v191, v190
	s_nop 0
	v_mul_f32_e32 v164, v164, v191
; __device__ __forceinline__ float bf2f(u16 v) { return __uint_as_float(((unsigned)v) << 16); }
; __device__ __forceinline__ float siluf_(float x) { return x / (1.f + __expf(-x)); }
; __device__ void phase_combine(const P& p, int l, int ntok, float* lds) {
;     ...
; #pragma unroll
;       for (int i = 0; i < 4; ++i) {
;         int row = r0 + i0 + i;
;         float o0 = bf2f((u16)a0[i]) + bf2f((u16)a1[i]), o1 = bf2f((u16)a2[i]) + bf2f((u16)a3[i]);
;         float ss = wave_sum_b(o0 * o0 + o1 * o1);
;         float rstd = rsqrtf(ss * (1.f / 128.f) + 1e-6f);
;         u16* dst = p.nbuf + (size_t)row * D + mixer * 512 + hh * 128 + lane;
;         dst[0] = f2bf(o0 * rstd * ng0 * siluf_(bf2f((u16)g0r[i])));
;         dst[64] = f2bf(o1 * rstd * ng1 * siluf_(bf2f((u16)g1r[i])));
;       }
; #pragma unroll
;       for (int i = 0; i < 4; ++i) {
;         int tr = (tb + i0 + i) & (RL - 1);
;         float up = tr != 0 ? bf2f((u16)ucc[i]) * bf2f((u16)uch[i]) : 0.f;
;         float uc = bf2f((u16)ucc[i + 1]) * bf2f((u16)uch[i + 1]);
;         float un = tr != RL - 1 ? bf2f((u16)ucc[i + 2]) * bf2f((u16)uch[i + 2]) : 0.f;
;         float cv = scw0 * up + scw1 * uc + scw2 * un;
;         p.nbuf[(size_t)(r0 + i0 + i) * D + 1024 + tid] = f2bf(bf2f((u16)cbr[i]) * cv);
;       }
	v_mul_f32_e32 v22, v164, v22
	v_bfe_u32 v164, v22, 16, 1
	v_lshl_add_u64 v[166:167], v[12:13], 0, s[42:43]
	v_add3_u32 v22, v22, v164, s21
	global_store_short_d16_hi v[166:167], v22, off
	v_mul_f32_e32 v22, v23, v165
	v_lshlrev_b32_e32 v23, 16, v163
	v_mul_f32_e32 v163, 0xbfb8aa3b, v23
	v_exp_f32_e32 v163, v163
	v_mul_f32_e32 v22, v127, v22
	v_add_f32_e32 v163, 1.0, v163
	s_nop 0
	v_rcp_f32_e32 v164, v163
	s_nop 0
	v_mul_f32_e32 v23, v23, v164
	v_mul_f32_e32 v22, v23, v22
	v_bfe_u32 v23, v22, 16, 1
	v_add3_u32 v22, v22, v23, s21
	global_store_short_d16_hi v[166:167], v22, off offset:128
	v_lshlrev_b32_e32 v22, 16, v161
	v_lshlrev_b32_e32 v23, 16, v162
	v_lshlrev_b32_e32 v162, 16, v159
	v_lshlrev_b32_e32 v163, 16, v160
	v_pk_add_f32 v[22:23], v[22:23], v[162:163]
	v_mul_f32_e32 v162, 0xbfb8aa3b, v158
	v_pk_mul_f32 v[160:161], v[22:23], v[22:23]
	v_exp_f32_e32 v162, v162
	v_add_f32_e32 v159, v160, v161
	v_mov_b32_e32 v160, v129
	v_add_f32_e32 v162, 1.0, v162
	v_add_f32_dpp v159, v159, v159 quad_perm:[1,0,3,2] row_mask:0xf bank_mask:0xf bound_ctrl:1
	s_nop 1
	v_add_f32_dpp v159, v159, v159 quad_perm:[2,3,0,1] row_mask:0xf bank_mask:0xf bound_ctrl:1
	s_nop 1
	v_add_f32_dpp v159, v159, v159 row_half_mirror row_mask:0xf bank_mask:0xf bound_ctrl:1
	s_nop 1
	v_add_f32_dpp v159, v159, v159 row_mirror row_mask:0xf bank_mask:0xf bound_ctrl:1
	s_nop 1
	v_mov_b32_dpp v160, v159 row_bcast:15 row_mask:0xa bank_mask:0xf
	v_add_f32_e32 v159, v159, v160
	v_mov_b32_e32 v160, v129
	s_nop 1
	v_mov_b32_dpp v160, v159 row_bcast:31 row_mask:0xc bank_mask:0xf
	v_add_f32_e32 v159, v159, v160
	s_nop 0
	v_readlane_b32 s20, v159, 63
	s_nop 1
	v_fma_f32 v159, s20, v182, v169
	v_cmp_gt_f32_e32 vcc, s33, v159
	v_mul_f32_e32 v160, 0x4b800000, v159
	s_nop 0
	v_cndmask_b32_e32 v159, v159, v160, vcc
	v_rsq_f32_e32 v159, v159
	s_nop 0
	v_mul_f32_e32 v160, 0x45800000, v159
	v_cndmask_b32_e32 v159, v159, v160, vcc
	v_lshl_add_u64 v[160:161], v[12:13], 0, s[2:3]
	v_mul_f32_e32 v22, v22, v159
	v_mul_f32_e32 v22, v126, v22
	v_rcp_f32_e32 v163, v162
	s_nop 0
	v_mul_f32_e32 v158, v158, v163
	v_mul_f32_e32 v22, v158, v22
	v_bfe_u32 v158, v22, 16, 1
	v_add3_u32 v22, v22, v158, s21
	global_store_short_d16_hi v[160:161], v22, off
	v_mul_f32_e32 v22, v23, v159
	v_lshlrev_b32_e32 v23, 16, v157
	v_mul_f32_e32 v157, 0xbfb8aa3b, v23
	v_exp_f32_e32 v157, v157
	v_mul_f32_e32 v22, v127, v22
	v_add_f32_e32 v157, 1.0, v157
	s_nop 0
	v_rcp_f32_e32 v158, v157
	s_nop 0
	v_mul_f32_e32 v23, v23, v158
	v_mul_f32_e32 v22, v23, v22
	v_bfe_u32 v23, v22, 16, 1
	v_add3_u32 v22, v22, v23, s21
	global_store_short_d16_hi v[160:161], v22, off offset:128
	v_lshlrev_b32_e32 v22, 16, v155
	v_lshlrev_b32_e32 v23, 16, v156
	v_lshlrev_b32_e32 v156, 16, v153
	v_lshlrev_b32_e32 v157, 16, v154
	v_pk_add_f32 v[22:23], v[22:23], v[156:157]
	v_mul_f32_e32 v156, 0xbfb8aa3b, v152
	v_pk_mul_f32 v[154:155], v[22:23], v[22:23]
	v_exp_f32_e32 v156, v156
	v_add_f32_e32 v153, v154, v155
	v_mov_b32_e32 v154, v129
	v_add_f32_e32 v156, 1.0, v156
	v_add_f32_dpp v153, v153, v153 quad_perm:[1,0,3,2] row_mask:0xf bank_mask:0xf bound_ctrl:1
	s_nop 1
	v_add_f32_dpp v153, v153, v153 quad_perm:[2,3,0,1] row_mask:0xf bank_mask:0xf bound_ctrl:1
	s_nop 1
	v_add_f32_dpp v153, v153, v153 row_half_mirror row_mask:0xf bank_mask:0xf bound_ctrl:1
	s_nop 1
	v_add_f32_dpp v153, v153, v153 row_mirror row_mask:0xf bank_mask:0xf bound_ctrl:1
	s_nop 1
	v_mov_b32_dpp v154, v153 row_bcast:15 row_mask:0xa bank_mask:0xf
	v_add_f32_e32 v153, v153, v154
	v_mov_b32_e32 v154, v129
	s_nop 1
	v_mov_b32_dpp v154, v153 row_bcast:31 row_mask:0xc bank_mask:0xf
	v_add_f32_e32 v153, v153, v154
	s_nop 0
	v_readlane_b32 s2, v153, 63
	s_nop 1
	v_fma_f32 v153, s2, v182, v169
	v_cmp_gt_f32_e32 vcc, s33, v153
	v_mul_f32_e32 v154, 0x4b800000, v153
	s_nop 0
	v_cndmask_b32_e32 v153, v153, v154, vcc
	v_rsq_f32_e32 v153, v153
	s_nop 0
	v_mul_f32_e32 v154, 0x45800000, v153
	v_cndmask_b32_e32 v153, v153, v154, vcc
	v_lshl_add_u64 v[154:155], v[12:13], 0, s[0:1]
	v_mul_f32_e32 v22, v22, v153
	v_mul_f32_e32 v22, v126, v22
	v_rcp_f32_e32 v157, v156
	s_nop 0
	v_mul_f32_e32 v152, v152, v157
	v_mul_f32_e32 v22, v152, v22
	v_bfe_u32 v152, v22, 16, 1
	v_add3_u32 v22, v22, v152, s21
	global_store_short_d16_hi v[154:155], v22, off
	v_mul_f32_e32 v22, v23, v153
	v_lshlrev_b32_e32 v23, 16, v149
	v_mul_f32_e32 v149, 0xbfb8aa3b, v23
	v_exp_f32_e32 v149, v149
	v_mul_f32_e32 v22, v127, v22
	v_add_f32_e32 v149, 1.0, v149
	s_and_b32 s0, s46, s58
	s_cmp_lg_u32 s0, 0
	v_rcp_f32_e32 v152, v149
	s_nop 0
	v_mul_f32_e32 v23, v23, v152
	v_mul_f32_e32 v22, v23, v22
	v_bfe_u32 v23, v22, 16, 1
	v_add3_u32 v22, v22, v23, s21
	global_store_short_d16_hi v[154:155], v22, off offset:128
	v_lshlrev_b32_e32 v22, 16, v139
	v_lshlrev_b32_e32 v23, 16, v140
	v_mul_f32_e32 v22, v22, v23
	s_cselect_b64 vcc, -1, 0
	v_cndmask_b32_e32 v22, 0, v22, vcc
	v_lshlrev_b32_e32 v23, 16, v147
	v_lshlrev_b32_e32 v139, 16, v148
	v_mul_f32_e32 v23, v23, v139
	v_lshlrev_b32_e32 v139, 16, v150
	v_lshlrev_b32_e32 v140, 16, v151
	v_mul_f32_e32 v22, v123, v22
	v_mul_f32_e32 v139, v139, v140
	v_fmac_f32_e32 v22, v124, v23
	v_fmac_f32_e32 v22, v125, v139
	v_mul_f32_e32 v22, v22, v138
	v_bfe_u32 v138, v22, 16, 1
	v_add3_u32 v22, v22, v138, s21
	global_store_short_d16_hi v[18:19], v22, off offset:2048
	v_lshlrev_b32_e32 v18, 16, v145
	v_lshlrev_b32_e32 v19, 16, v146
	v_mul_f32_e32 v18, v18, v19
	v_mul_f32_e32 v19, v124, v139
	v_fmac_f32_e32 v19, v123, v23
	v_fmac_f32_e32 v19, v125, v18
	v_lshlrev_b32_e32 v22, 16, v137
	v_mul_f32_e32 v19, v19, v22
	v_bfe_u32 v22, v19, 16, 1
	v_add3_u32 v19, v19, v22, s21
	global_store_short_d16_hi v[20:21], v19, off offset:2048
	v_lshlrev_b32_e32 v19, 16, v143
	v_lshlrev_b32_e32 v20, 16, v144
	v_mul_f32_e32 v19, v19, v20
	v_mul_f32_e32 v20, v124, v18
	v_fmac_f32_e32 v20, v123, v139
	v_fmac_f32_e32 v20, v125, v19
	v_lshlrev_b32_e32 v21, 16, v136
	v_mul_f32_e32 v20, v20, v21
	v_bfe_u32 v21, v20, 16, 1
	v_add3_u32 v20, v20, v21, s21
	s_and_b32 s0, s36, s58
	global_store_short_d16_hi v[2:3], v20, off offset:2048
	v_lshlrev_b32_e32 v2, 16, v141
	v_lshlrev_b32_e32 v3, 16, v142
	s_cmp_lg_u32 s0, s58
	v_mul_f32_e32 v2, v2, v3
	s_cselect_b64 vcc, -1, 0
	v_mul_f32_e32 v3, v124, v19
	v_cndmask_b32_e32 v2, 0, v2, vcc
	v_fmac_f32_e32 v3, v123, v18
	v_fmac_f32_e32 v3, v125, v2
	v_lshlrev_b32_e32 v2, 16, v135
	v_mul_f32_e32 v2, v3, v2
	v_bfe_u32 v3, v2, 16, 1
	s_add_i32 s0, s60, 4
	v_add3_u32 v2, v2, v3, s21
	s_cmp_gt_u32 s60, 11
	s_mov_b32 s60, s0
	global_store_short_d16_hi v[0:1], v2, off offset:2048
	s_cbranch_scc0 .LBB0_94
	v_readlane_b32 s0, v240, 4
	v_readlane_b32 s1, v240, 5
	s_load_dword s0, s[0:1], 0x0
	s_movk_i32 s33, 0x3600
	s_waitcnt lgkmcnt(0)
	s_add_i32 s55, s0, s55
	s_cmp_ge_i32 s55, s72
	s_cbranch_scc0 .LBB0_90
